# v51 + non-temporal hint on all P1 in-projection epilogue stores (outputs are consumed phases later; keeps them from displacing the A/B tiles in L2)
# baseline (speedup 1.0000x reference)
;     __device__ __forceinline__ void operator()(const Acc& acc, const Unit& u, int wr, int wc, int fr, int fq) const {
;     ...
;             const int blk = u.pn * 2 + bj;
;             if (blk >= 77) continue;
;             bf16_t* base; size_t bstride; int kind = 0;
;             if (blk < 8)       { base = (bf16_t*)(ws + WS_QN) + (size_t)blk * SEQ * 128; bstride = (size_t)8 * SEQ * 128; }
;             else if (blk < 10) { base = (bf16_t*)(ws + WS_KC) + (size_t)(blk - 8) * KCROWS * 128; bstride = (size_t)2 * KCROWS * 128; }
;             else if (blk < 12) { base = (bf16_t*)(ws + WS_VC) + (size_t)(blk - 10) * KCROWS * 128; bstride = (size_t)2 * KCROWS * 128; }
;             else if (blk < 14) { base = (bf16_t*)(ws + WS_KSL) + (size_t)(blk - 12) * SEQ * 128; bstride = (size_t)2 * SEQ * 128; }
;             else if (blk < 16) { base = (bf16_t*)(ws + WS_VSL) + (size_t)(blk - 14) * SEQ * 128; bstride = (size_t)2 * SEQ * 128; }
;             else if (blk < 18) { base = (bf16_t*)(ws + WS_KW) + (size_t)(blk - 16) * SEQ * 128; bstride = (size_t)2 * SEQ * 128; }
;             else if (blk < 20) { base = (bf16_t*)(ws + WS_VW) + (size_t)(blk - 18) * SEQ * 128; bstride = (size_t)2 * SEQ * 128; }
;             else if (blk < 28) { base = (bf16_t*)(ws + WS_QD) + (size_t)(blk - 20) * SEQ * 128; bstride = (size_t)8 * SEQ * 128; }
;             else if (blk < 36) { base = (bf16_t*)(ws + WS_KD) + (size_t)(blk - 28) * SEQ * 128; bstride = (size_t)8 * SEQ * 128; }
;             else if (blk < 44) { base = (bf16_t*)(ws + WS_VD) + (size_t)(blk - 36) * SEQ * 128; bstride = (size_t)8 * SEQ * 128; }
;             else if (blk < 76) { base = (bf16_t*)(ws + WS_GM) + (size_t)(blk - 44) * 128; bstride = 0; kind = 1; }
;             else               { base = nullptr; bstride = 0; kind = 2; }
; #pragma unroll
;             for (int ai = 0; ai < 2; ++ai)
; #pragma unroll
;                 for (int m = 0; m < 4; ++m) {
;                     const int row = u.pm * 256 + ai * 128 + wr * 64 + m * 16 + fr;
;                     f32x4 v0 = acc[ai][bj][m][0], v1 = acc[ai][bj][m][1];
;                     if (kind == 0) {
;                         const int b = row >> 14, s = row & (SEQ - 1);
;                         *(u32x4*)(base + (size_t)b * bstride + (size_t)s * 128 + d) = pack8v(v0, v1);
;                     } else if (kind == 1) {
; #pragma unroll
.LBB0_200:
	s_xor_b64 s[62:63], s[10:11], -1
	s_mul_i32 s10, s58, s72
	s_mul_hi_u32 s11, s58, s49
	s_add_i32 s10, s11, s10
	s_mul_i32 s11, s59, s49
	s_add_i32 s11, s10, s11
	s_mul_i32 s10, s58, s49
	s_xor_b64 s[60:61], s[60:61], -1
	v_lshlrev_b32_e32 v136, 1, v138
	s_lshl_b64 s[10:11], s[10:11], 1
	v_lshl_add_u64 v[152:153], s[8:9], 0, v[136:137]
	s_add_u32 s8, s8, s10
	s_mov_b64 s[64:65], -1
	s_addc_u32 s9, s9, s11
	s_and_b64 vcc, exec, s[60:61]
	s_cbranch_vccz .LBB0_208
	s_mov_b64 s[10:11], -1
	s_and_b64 vcc, exec, s[62:63]
	s_cbranch_vccz .LBB0_205
	s_and_saveexec_b64 s[10:11], s[4:5]
	s_cbranch_execz .LBB0_204
	v_mul_f32_e32 v151, 0xbfb8aa3b, v124
	v_exp_f32_e32 v151, v151
	v_mul_f32_e32 v154, 0xbfb8aa3b, v120
	v_exp_f32_e32 v154, v154
	v_mul_f32_e32 v155, 0xbfb8aa3b, v121
	v_add_f32_e32 v151, 1.0, v151
	v_rcp_f32_e32 v160, v151
	v_mul_f32_e32 v151, 0xbfb8aa3b, v125
	v_exp_f32_e32 v151, v151
	v_exp_f32_e32 v155, v155
	v_add_f32_e32 v154, 1.0, v154
	v_rcp_f32_e32 v164, v154
	v_add_f32_e32 v151, 1.0, v151
	v_mul_f32_e32 v154, 0xbfb8aa3b, v126
	v_rcp_f32_e32 v161, v151
	v_add_f32_e32 v151, 1.0, v155
	v_exp_f32_e32 v154, v154
	v_mul_f32_e32 v155, 0xbfb8aa3b, v122
	v_exp_f32_e32 v155, v155
	v_rcp_f32_e32 v165, v151
	v_add_f32_e32 v151, 1.0, v154
	v_mul_f32_e32 v154, 0xbfb8aa3b, v127
	v_rcp_f32_e32 v162, v151
	v_add_f32_e32 v151, 1.0, v155
	v_exp_f32_e32 v154, v154
	v_mul_f32_e32 v155, 0xbfb8aa3b, v123
	v_exp_f32_e32 v155, v155
	v_rcp_f32_e32 v166, v151
	v_add_f32_e32 v151, 1.0, v154
	v_rcp_f32_e32 v163, v151
	v_add_f32_e32 v151, 1.0, v155
	v_rcp_f32_e32 v167, v151
	v_mad_i64_i32 v[154:155], s[20:21], v150, s27, v[140:141]
	global_store_dwordx4 v[154:155], v[160:163], off nt
	global_store_dwordx4 v[154:155], v[164:167], off offset:16 nt

; __device__ __forceinline__ u32x4 pack8v(f32x4 a, f32x4 b) { u32x4 w; w.x = cvtpk(a[0], a[1]); w.y = cvtpk(a[2], a[3]); w.z = cvtpk(b[0], b[1]); w.w = cvtpk(b[2], b[3]); return w; }
;     __device__ __forceinline__ void operator()(const Acc& acc, const Unit& u, int wr, int wc, int fr, int fq) const {
;     ...
;                     if (kind == 0) {
;                         const int b = row >> 14, s = row & (SEQ - 1);
;                         *(u32x4*)(base + (size_t)b * bstride + (size_t)s * 128 + d) = pack8v(v0, v1);
.LBB0_208:
	s_andn2_b64 vcc, exec, s[64:65]
	v_lshl_add_u64 v[154:155], s[8:9], 0, v[136:137]
	s_cbranch_vccnz .LBB0_210
	v_cvt_pk_bf16_f32 v124, v124, v125
	v_cvt_pk_bf16_f32 v125, v126, v127
	v_cvt_pk_bf16_f32 v126, v120, v121
	v_lshlrev_b32_e32 v120, 8, v150
	v_and_b32_e32 v136, 0x3f4f00, v120
	v_lshl_add_u64 v[120:121], v[154:155], 0, v[136:137]
	v_cvt_pk_bf16_f32 v127, v122, v123
	global_store_dwordx4 v[120:121], v[124:127], off nt

; __device__ __forceinline__ u32x4 pack8v(f32x4 a, f32x4 b) { u32x4 w; w.x = cvtpk(a[0], a[1]); w.y = cvtpk(a[2], a[3]); w.z = cvtpk(b[0], b[1]); w.w = cvtpk(b[2], b[3]); return w; }
;     __device__ __forceinline__ void operator()(const Acc& acc, const Unit& u, int wr, int wc, int fr, int fq) const {
;     ...
;                     if (kind == 0) {
;                         const int b = row >> 14, s = row & (SEQ - 1);
;                         *(u32x4*)(base + (size_t)b * bstride + (size_t)s * 128 + d) = pack8v(v0, v1);
.LBB0_224:
	v_cvt_pk_bf16_f32 v68, v68, v69
	v_cvt_pk_bf16_f32 v69, v70, v71
	v_cvt_pk_bf16_f32 v70, v64, v65
	v_lshlrev_b32_e32 v64, 8, v72
	v_and_b32_e32 v136, 0x3fff00, v64
	v_lshl_add_u64 v[64:65], v[154:155], 0, v[136:137]
	v_cvt_pk_bf16_f32 v71, v66, v67
	global_store_dwordx4 v[64:65], v[68:71], off nt

;     __device__ __forceinline__ void operator()(const Acc& acc, const Unit& u, int wr, int wc, int fr, int fq) const {
;     ...
;             const int blk = u.pn * 2 + bj;
;             if (blk >= 77) continue;
;             bf16_t* base; size_t bstride; int kind = 0;
;             if (blk < 8)       { base = (bf16_t*)(ws + WS_QN) + (size_t)blk * SEQ * 128; bstride = (size_t)8 * SEQ * 128; }
;             else if (blk < 10) { base = (bf16_t*)(ws + WS_KC) + (size_t)(blk - 8) * KCROWS * 128; bstride = (size_t)2 * KCROWS * 128; }
;             else if (blk < 12) { base = (bf16_t*)(ws + WS_VC) + (size_t)(blk - 10) * KCROWS * 128; bstride = (size_t)2 * KCROWS * 128; }
;             else if (blk < 14) { base = (bf16_t*)(ws + WS_KSL) + (size_t)(blk - 12) * SEQ * 128; bstride = (size_t)2 * SEQ * 128; }
;             else if (blk < 16) { base = (bf16_t*)(ws + WS_VSL) + (size_t)(blk - 14) * SEQ * 128; bstride = (size_t)2 * SEQ * 128; }
;             else if (blk < 18) { base = (bf16_t*)(ws + WS_KW) + (size_t)(blk - 16) * SEQ * 128; bstride = (size_t)2 * SEQ * 128; }
;             else if (blk < 20) { base = (bf16_t*)(ws + WS_VW) + (size_t)(blk - 18) * SEQ * 128; bstride = (size_t)2 * SEQ * 128; }
;             else if (blk < 28) { base = (bf16_t*)(ws + WS_QD) + (size_t)(blk - 20) * SEQ * 128; bstride = (size_t)8 * SEQ * 128; }
;             else if (blk < 36) { base = (bf16_t*)(ws + WS_KD) + (size_t)(blk - 28) * SEQ * 128; bstride = (size_t)8 * SEQ * 128; }
;             else if (blk < 44) { base = (bf16_t*)(ws + WS_VD) + (size_t)(blk - 36) * SEQ * 128; bstride = (size_t)8 * SEQ * 128; }
;             else if (blk < 76) { base = (bf16_t*)(ws + WS_GM) + (size_t)(blk - 44) * 128; bstride = 0; kind = 1; }
;             else               { base = nullptr; bstride = 0; kind = 2; }
; #pragma unroll
;             for (int ai = 0; ai < 2; ++ai)
; #pragma unroll
;                 for (int m = 0; m < 4; ++m) {
;                     const int row = u.pm * 256 + ai * 128 + wr * 64 + m * 16 + fr;
;                     f32x4 v0 = acc[ai][bj][m][0], v1 = acc[ai][bj][m][1];
;                     if (kind == 0) {
;                         const int b = row >> 14, s = row & (SEQ - 1);
;                         *(u32x4*)(base + (size_t)b * bstride + (size_t)s * 128 + d) = pack8v(v0, v1);
;                     } else if (kind == 1) {
; #pragma unroll
.LBB0_265:
	s_mul_i32 s20, s60, s72
	s_mul_hi_u32 s21, s60, s49
	s_add_i32 s20, s21, s20
	s_mul_i32 s21, s61, s49
	s_add_i32 s21, s20, s21
	s_mul_i32 s20, s60, s49
	s_xor_b64 s[8:9], s[58:59], -1
	v_lshlrev_b32_e32 v136, 1, v138
	s_lshl_b64 s[20:21], s[20:21], 1
	v_lshl_add_u64 v[64:65], s[54:55], 0, v[136:137]
	s_add_u32 s54, s54, s20
	v_cndmask_b32_e64 v66, 0, 1, s[8:9]
	s_mov_b64 s[56:57], -1
	s_addc_u32 s55, s55, s21
	s_and_b64 vcc, exec, s[10:11]
	v_cmp_ne_u32_e64 s[8:9], 1, v66
	s_cbranch_vccnz .LBB0_273
	s_and_b64 vcc, exec, s[8:9]
	s_cbranch_vccnz .LBB0_270
	s_and_saveexec_b64 s[56:57], s[4:5]
	s_cbranch_execz .LBB0_269
	v_mul_f32_e32 v67, 0xbfb8aa3b, v56
	v_exp_f32_e32 v67, v67
	v_mul_f32_e32 v68, 0xbfb8aa3b, v61
	v_mul_f32_e32 v69, 0xbfb8aa3b, v57
	v_exp_f32_e32 v68, v68
	v_exp_f32_e32 v69, v69
	v_add_f32_e32 v67, 1.0, v67
	v_rcp_f32_e32 v70, v67
	v_add_f32_e32 v67, 1.0, v68
	v_add_f32_e32 v68, 1.0, v69
	v_mul_f32_e32 v69, 0xbfb8aa3b, v62
	v_mul_f32_e32 v71, 0xbfb8aa3b, v58
	v_exp_f32_e32 v69, v69
	v_exp_f32_e32 v72, v71
	v_mul_f32_e32 v66, 0xbfb8aa3b, v60
	v_rcp_f32_e32 v71, v68
	v_add_f32_e32 v68, 1.0, v69
	v_add_f32_e32 v69, 1.0, v72
	v_mul_f32_e32 v72, 0xbfb8aa3b, v63
	v_exp_f32_e32 v66, v66
	v_exp_f32_e32 v73, v72
	v_mul_f32_e32 v72, 0xbfb8aa3b, v59
	v_exp_f32_e32 v74, v72
	v_add_f32_e32 v66, 1.0, v66
	v_rcp_f32_e32 v72, v69
	v_add_f32_e32 v69, 1.0, v73
	v_rcp_f32_e32 v66, v66
	v_rcp_f32_e32 v67, v67
	v_rcp_f32_e32 v68, v68
	v_rcp_f32_e32 v69, v69
	v_add_f32_e32 v73, 1.0, v74
	v_rcp_f32_e32 v73, v73
	v_mad_i64_i32 v[74:75], s[20:21], v150, s27, v[140:141]
	global_store_dwordx4 v[74:75], v[66:69], off nt
	global_store_dwordx4 v[74:75], v[70:73], off offset:16 nt

; __device__ __forceinline__ u32x4 pack8v(f32x4 a, f32x4 b) { u32x4 w; w.x = cvtpk(a[0], a[1]); w.y = cvtpk(a[2], a[3]); w.z = cvtpk(b[0], b[1]); w.w = cvtpk(b[2], b[3]); return w; }
;     __device__ __forceinline__ void operator()(const Acc& acc, const Unit& u, int wr, int wc, int fr, int fq) const {
;     ...
;                     if (kind == 0) {
;                         const int b = row >> 14, s = row & (SEQ - 1);
;                         *(u32x4*)(base + (size_t)b * bstride + (size_t)s * 128 + d) = pack8v(v0, v1);
.LBB0_273:
	s_andn2_b64 vcc, exec, s[56:57]
	v_lshl_add_u64 v[66:67], s[54:55], 0, v[136:137]
	s_cbranch_vccnz .LBB0_275
	v_cvt_pk_bf16_f32 v60, v60, v61
	v_cvt_pk_bf16_f32 v61, v62, v63
	v_cvt_pk_bf16_f32 v62, v56, v57
	v_lshlrev_b32_e32 v56, 8, v150
	v_and_b32_e32 v136, 0x3f4f00, v56
	v_lshl_add_u64 v[56:57], v[66:67], 0, v[136:137]
	v_cvt_pk_bf16_f32 v63, v58, v59
	global_store_dwordx4 v[56:57], v[60:63], off nt

; __device__ __forceinline__ u32x4 pack8v(f32x4 a, f32x4 b) { u32x4 w; w.x = cvtpk(a[0], a[1]); w.y = cvtpk(a[2], a[3]); w.z = cvtpk(b[0], b[1]); w.w = cvtpk(b[2], b[3]); return w; }
;     __device__ __forceinline__ void operator()(const Acc& acc, const Unit& u, int wr, int wc, int fr, int fq) const {
;     ...
;                     if (kind == 0) {
;                         const int b = row >> 14, s = row & (SEQ - 1);
;                         *(u32x4*)(base + (size_t)b * bstride + (size_t)s * 128 + d) = pack8v(v0, v1);
.LBB0_289:
	v_cvt_pk_bf16_f32 v4, v4, v5
	v_cvt_pk_bf16_f32 v5, v6, v7
	v_cvt_pk_bf16_f32 v6, v0, v1
	v_lshlrev_b32_e32 v0, 8, v8
	v_and_b32_e32 v136, 0x3fff00, v0
	v_lshl_add_u64 v[0:1], v[66:67], 0, v[136:137]
	v_cvt_pk_bf16_f32 v7, v2, v3
	global_store_dwordx4 v[0:1], v[4:7], off nt

; __device__ __forceinline__ float sigmoidf_(float x) { return __builtin_amdgcn_rcpf(1.f + __builtin_amdgcn_exp2f(-1.4426950408889634f * x)); }
;     __device__ __forceinline__ void operator()(const Acc& acc, const Unit& u, int wr, int wc, int fr, int fq) const {
;     ...
;                         if (d < 24) { float* gn = (float*)(ws + WS_GN) + (size_t)row * 24 + d;
; #pragma unroll
;                             for (int e = 0; e < 4; ++e) { v0[e] = sigmoidf_(v0[e]); v1[e] = sigmoidf_(v1[e]); }
;                             *(f32x4*)gn = v0; *(f32x4*)(gn + 4) = v1; }
.LBB0_293:
	s_and_b64 vcc, exec, s[8:9]
	s_cbranch_vccnz .LBB0_297
	s_and_saveexec_b64 s[58:59], s[4:5]
	s_cbranch_execz .LBB0_296
	v_mul_f32_e32 v121, 0xbfb8aa3b, v116
	v_exp_f32_e32 v121, v121
	v_mul_f32_e32 v122, 0xbfb8aa3b, v112
	v_exp_f32_e32 v122, v122
	v_mul_f32_e32 v124, 0xbfb8aa3b, v113
	v_add_f32_e32 v121, 1.0, v121
	v_exp_f32_e32 v124, v124
	v_add_f32_e32 v123, 1.0, v122
	v_rcp_f32_e32 v122, v121
	v_mul_f32_e32 v121, 0xbfb8aa3b, v117
	v_exp_f32_e32 v121, v121
	v_rcp_f32_e32 v160, v123
	v_mul_f32_e32 v125, 0xbfb8aa3b, v114
	v_exp_f32_e32 v125, v125
	v_add_f32_e32 v121, 1.0, v121
	v_rcp_f32_e32 v123, v121
	v_add_f32_e32 v121, 1.0, v124
	v_mul_f32_e32 v124, 0xbfb8aa3b, v118
	v_exp_f32_e32 v124, v124
	v_rcp_f32_e32 v161, v121
	v_mul_f32_e32 v126, 0xbfb8aa3b, v115
	v_exp_f32_e32 v126, v126
	v_add_f32_e32 v121, 1.0, v124
	v_rcp_f32_e32 v124, v121
	v_add_f32_e32 v121, 1.0, v125
	v_mul_f32_e32 v125, 0xbfb8aa3b, v119
	v_exp_f32_e32 v125, v125
	v_rcp_f32_e32 v162, v121
	v_add_f32_e32 v121, 1.0, v125
	v_rcp_f32_e32 v125, v121
	v_add_f32_e32 v121, 1.0, v126
	v_rcp_f32_e32 v163, v121
	v_mad_i64_i32 v[126:127], s[20:21], v120, s27, v[140:141]
	global_store_dwordx4 v[126:127], v[122:125], off nt
	global_store_dwordx4 v[126:127], v[160:163], off offset:16 nt

; __device__ __forceinline__ float sigmoidf_(float x) { return __builtin_amdgcn_rcpf(1.f + __builtin_amdgcn_exp2f(-1.4426950408889634f * x)); }
; __device__ __forceinline__ u32x4 pack8v(f32x4 a, f32x4 b) { u32x4 w; w.x = cvtpk(a[0], a[1]); w.y = cvtpk(a[2], a[3]); w.z = cvtpk(b[0], b[1]); w.w = cvtpk(b[2], b[3]); return w; }
;     __device__ __forceinline__ void operator()(const Acc& acc, const Unit& u, int wr, int wc, int fr, int fq) const {
;     ...
;                     if (kind == 0) {
;                         const int b = row >> 14, s = row & (SEQ - 1);
;                         *(u32x4*)(base + (size_t)b * bstride + (size_t)s * 128 + d) = pack8v(v0, v1);
;                     } else if (kind == 1) {
; #pragma unroll
;                         for (int e = 0; e < 4; ++e) { v0[e] = sigmoidf_(v0[e]); v1[e] = sigmoidf_(v1[e]); }
;                         __builtin_nontemporal_store(pack8v(v0, v1), (u32x4*)(base + (size_t)row * 4096 + d));
;                     } else {
;                         if (d < 24) { float* gn = (float*)(ws + WS_GN) + (size_t)row * 24 + d;
; #pragma unroll
;                             for (int e = 0; e < 4; ++e) { v0[e] = sigmoidf_(v0[e]); v1[e] = sigmoidf_(v1[e]); }
;                             *(f32x4*)gn = v0; *(f32x4*)(gn + 4) = v1; }
.LBB0_300:
	v_cvt_pk_bf16_f32 v116, v116, v117
	v_cvt_pk_bf16_f32 v117, v118, v119
	v_cvt_pk_bf16_f32 v118, v112, v113
	v_lshlrev_b32_e32 v112, 8, v120
	v_and_b32_e32 v136, 0x3f5f00, v112
	v_lshl_add_u64 v[112:113], v[154:155], 0, v[136:137]
	v_cvt_pk_bf16_f32 v119, v114, v115
	global_store_dwordx4 v[112:113], v[116:119], off nt
	v_or_b32_e32 v112, 32, v150
	s_and_b64 vcc, exec, s[10:11]
	s_mov_b64 s[58:59], -1
	s_cbranch_vccnz .LBB0_213
.LBB0_301:
	s_and_b64 vcc, exec, s[8:9]
	s_cbranch_vccnz .LBB0_305
	s_and_saveexec_b64 s[58:59], s[4:5]
	s_cbranch_execz .LBB0_304
	v_mul_f32_e32 v113, 0xbfb8aa3b, v108
	v_exp_f32_e32 v113, v113
	v_mul_f32_e32 v114, 0xbfb8aa3b, v104
	v_exp_f32_e32 v114, v114
	v_mul_f32_e32 v116, 0xbfb8aa3b, v105
	v_add_f32_e32 v113, 1.0, v113
	v_exp_f32_e32 v116, v116
	v_add_f32_e32 v115, 1.0, v114
	v_rcp_f32_e32 v114, v113
	v_mul_f32_e32 v113, 0xbfb8aa3b, v109
	v_exp_f32_e32 v113, v113
	v_rcp_f32_e32 v118, v115
	v_mul_f32_e32 v117, 0xbfb8aa3b, v106
	v_exp_f32_e32 v117, v117
	v_add_f32_e32 v113, 1.0, v113
	v_rcp_f32_e32 v115, v113
	v_add_f32_e32 v113, 1.0, v116
	v_mul_f32_e32 v116, 0xbfb8aa3b, v110
	v_exp_f32_e32 v116, v116
	v_rcp_f32_e32 v119, v113
	v_mul_f32_e32 v120, 0xbfb8aa3b, v107
	v_exp_f32_e32 v121, v120
	v_add_f32_e32 v113, 1.0, v116
	v_rcp_f32_e32 v116, v113
	v_add_f32_e32 v113, 1.0, v117
	v_mul_f32_e32 v117, 0xbfb8aa3b, v111
	v_exp_f32_e32 v117, v117
	v_rcp_f32_e32 v120, v113
	v_mad_i64_i32 v[122:123], s[20:21], v112, s27, v[140:141]
	v_add_f32_e32 v113, 1.0, v117
	v_rcp_f32_e32 v117, v113
	v_add_f32_e32 v113, 1.0, v121
	v_rcp_f32_e32 v121, v113
	global_store_dwordx4 v[122:123], v[114:117], off nt
	global_store_dwordx4 v[122:123], v[118:121], off offset:16 nt

; __device__ __forceinline__ float sigmoidf_(float x) { return __builtin_amdgcn_rcpf(1.f + __builtin_amdgcn_exp2f(-1.4426950408889634f * x)); }
; __device__ __forceinline__ u32x4 pack8v(f32x4 a, f32x4 b) { u32x4 w; w.x = cvtpk(a[0], a[1]); w.y = cvtpk(a[2], a[3]); w.z = cvtpk(b[0], b[1]); w.w = cvtpk(b[2], b[3]); return w; }
;     __device__ __forceinline__ void operator()(const Acc& acc, const Unit& u, int wr, int wc, int fr, int fq) const {
;     ...
;                     if (kind == 0) {
;                         const int b = row >> 14, s = row & (SEQ - 1);
;                         *(u32x4*)(base + (size_t)b * bstride + (size_t)s * 128 + d) = pack8v(v0, v1);
;                     } else if (kind == 1) {
; #pragma unroll
;                         for (int e = 0; e < 4; ++e) { v0[e] = sigmoidf_(v0[e]); v1[e] = sigmoidf_(v1[e]); }
;                         __builtin_nontemporal_store(pack8v(v0, v1), (u32x4*)(base + (size_t)row * 4096 + d));
;                     } else {
;                         if (d < 24) { float* gn = (float*)(ws + WS_GN) + (size_t)row * 24 + d;
; #pragma unroll
;                             for (int e = 0; e < 4; ++e) { v0[e] = sigmoidf_(v0[e]); v1[e] = sigmoidf_(v1[e]); }
;                             *(f32x4*)gn = v0; *(f32x4*)(gn + 4) = v1; }
.LBB0_308:
	v_cvt_pk_bf16_f32 v108, v108, v109
	v_cvt_pk_bf16_f32 v109, v110, v111
	v_cvt_pk_bf16_f32 v110, v104, v105
	v_lshlrev_b32_e32 v104, 8, v112
	v_and_b32_e32 v136, 0x3f6f00, v104
	v_lshl_add_u64 v[104:105], v[154:155], 0, v[136:137]
	v_cvt_pk_bf16_f32 v111, v106, v107
	global_store_dwordx4 v[104:105], v[108:111], off nt
	v_or_b32_e32 v104, 48, v150
	s_and_b64 vcc, exec, s[10:11]
	s_mov_b64 s[58:59], -1
	s_cbranch_vccnz .LBB0_215
.LBB0_309:
	s_and_b64 vcc, exec, s[8:9]
	s_cbranch_vccnz .LBB0_313
	s_and_saveexec_b64 s[58:59], s[4:5]
	s_cbranch_execz .LBB0_312
	v_mul_f32_e32 v105, 0xbfb8aa3b, v100
	v_exp_f32_e32 v105, v105
	v_mul_f32_e32 v106, 0xbfb8aa3b, v96
	v_exp_f32_e32 v106, v106
	v_mul_f32_e32 v108, 0xbfb8aa3b, v97
	v_add_f32_e32 v105, 1.0, v105
	v_exp_f32_e32 v108, v108
	v_add_f32_e32 v107, 1.0, v106
	v_rcp_f32_e32 v106, v105
	v_mul_f32_e32 v105, 0xbfb8aa3b, v101
	v_exp_f32_e32 v105, v105
	v_rcp_f32_e32 v110, v107
	v_mul_f32_e32 v109, 0xbfb8aa3b, v98
	v_exp_f32_e32 v109, v109
	v_add_f32_e32 v105, 1.0, v105
	v_rcp_f32_e32 v107, v105
	v_add_f32_e32 v105, 1.0, v108
	v_mul_f32_e32 v108, 0xbfb8aa3b, v102
	v_exp_f32_e32 v108, v108
	v_rcp_f32_e32 v111, v105
	v_mul_f32_e32 v112, 0xbfb8aa3b, v99
	v_exp_f32_e32 v113, v112
	v_add_f32_e32 v105, 1.0, v108
	v_rcp_f32_e32 v108, v105
	v_add_f32_e32 v105, 1.0, v109
	v_mul_f32_e32 v109, 0xbfb8aa3b, v103
	v_exp_f32_e32 v109, v109
	v_rcp_f32_e32 v112, v105
	v_mad_i64_i32 v[114:115], s[20:21], v104, s27, v[140:141]
	v_add_f32_e32 v105, 1.0, v109
	v_rcp_f32_e32 v109, v105
	v_add_f32_e32 v105, 1.0, v113
	v_rcp_f32_e32 v113, v105
	global_store_dwordx4 v[114:115], v[106:109], off nt
	global_store_dwordx4 v[114:115], v[110:113], off offset:16 nt

; __device__ __forceinline__ float sigmoidf_(float x) { return __builtin_amdgcn_rcpf(1.f + __builtin_amdgcn_exp2f(-1.4426950408889634f * x)); }
; __device__ __forceinline__ u32x4 pack8v(f32x4 a, f32x4 b) { u32x4 w; w.x = cvtpk(a[0], a[1]); w.y = cvtpk(a[2], a[3]); w.z = cvtpk(b[0], b[1]); w.w = cvtpk(b[2], b[3]); return w; }
;     __device__ __forceinline__ void operator()(const Acc& acc, const Unit& u, int wr, int wc, int fr, int fq) const {
;     ...
;                     if (kind == 0) {
;                         const int b = row >> 14, s = row & (SEQ - 1);
;                         *(u32x4*)(base + (size_t)b * bstride + (size_t)s * 128 + d) = pack8v(v0, v1);
;                     } else if (kind == 1) {
; #pragma unroll
;                         for (int e = 0; e < 4; ++e) { v0[e] = sigmoidf_(v0[e]); v1[e] = sigmoidf_(v1[e]); }
;                         __builtin_nontemporal_store(pack8v(v0, v1), (u32x4*)(base + (size_t)row * 4096 + d));
;                     } else {
;                         if (d < 24) { float* gn = (float*)(ws + WS_GN) + (size_t)row * 24 + d;
; #pragma unroll
;                             for (int e = 0; e < 4; ++e) { v0[e] = sigmoidf_(v0[e]); v1[e] = sigmoidf_(v1[e]); }
;                             *(f32x4*)gn = v0; *(f32x4*)(gn + 4) = v1; }
.LBB0_316:
	v_cvt_pk_bf16_f32 v100, v100, v101
	v_cvt_pk_bf16_f32 v101, v102, v103
	v_cvt_pk_bf16_f32 v102, v96, v97
	v_lshlrev_b32_e32 v96, 8, v104
	v_and_b32_e32 v136, 0x3f7f00, v96
	v_lshl_add_u64 v[96:97], v[154:155], 0, v[136:137]
	v_cvt_pk_bf16_f32 v103, v98, v99
	global_store_dwordx4 v[96:97], v[100:103], off nt
	v_or_b32_e32 v96, 0x80, v150
	s_and_b64 vcc, exec, s[10:11]
	s_mov_b64 s[58:59], -1
	s_cbranch_vccnz .LBB0_217
.LBB0_317:
	s_and_b64 vcc, exec, s[8:9]
	s_cbranch_vccnz .LBB0_321
	s_and_saveexec_b64 s[58:59], s[4:5]
	s_cbranch_execz .LBB0_320
	v_mul_f32_e32 v97, 0xbfb8aa3b, v92
	v_exp_f32_e32 v97, v97
	v_mul_f32_e32 v98, 0xbfb8aa3b, v88
	v_exp_f32_e32 v98, v98
	v_mul_f32_e32 v100, 0xbfb8aa3b, v89
	v_add_f32_e32 v97, 1.0, v97
	v_exp_f32_e32 v100, v100
	v_add_f32_e32 v99, 1.0, v98
	v_rcp_f32_e32 v98, v97
	v_mul_f32_e32 v97, 0xbfb8aa3b, v93
	v_exp_f32_e32 v97, v97
	v_rcp_f32_e32 v102, v99
	v_mul_f32_e32 v101, 0xbfb8aa3b, v90
	v_exp_f32_e32 v101, v101
	v_add_f32_e32 v97, 1.0, v97
	v_rcp_f32_e32 v99, v97
	v_add_f32_e32 v97, 1.0, v100
	v_mul_f32_e32 v100, 0xbfb8aa3b, v94
	v_exp_f32_e32 v100, v100
	v_rcp_f32_e32 v103, v97
	v_mul_f32_e32 v104, 0xbfb8aa3b, v91
	v_exp_f32_e32 v105, v104
	v_add_f32_e32 v97, 1.0, v100
	v_rcp_f32_e32 v100, v97
	v_add_f32_e32 v97, 1.0, v101
	v_mul_f32_e32 v101, 0xbfb8aa3b, v95
	v_exp_f32_e32 v101, v101
	v_rcp_f32_e32 v104, v97
	v_mad_i64_i32 v[106:107], s[20:21], v96, s27, v[140:141]
	v_add_f32_e32 v97, 1.0, v101
	v_rcp_f32_e32 v101, v97
	v_add_f32_e32 v97, 1.0, v105
	v_rcp_f32_e32 v105, v97
	global_store_dwordx4 v[106:107], v[98:101], off nt
	global_store_dwordx4 v[106:107], v[102:105], off offset:16 nt

; __device__ __forceinline__ float sigmoidf_(float x) { return __builtin_amdgcn_rcpf(1.f + __builtin_amdgcn_exp2f(-1.4426950408889634f * x)); }
; __device__ __forceinline__ u32x4 pack8v(f32x4 a, f32x4 b) { u32x4 w; w.x = cvtpk(a[0], a[1]); w.y = cvtpk(a[2], a[3]); w.z = cvtpk(b[0], b[1]); w.w = cvtpk(b[2], b[3]); return w; }
;     __device__ __forceinline__ void operator()(const Acc& acc, const Unit& u, int wr, int wc, int fr, int fq) const {
;     ...
;                     if (kind == 0) {
;                         const int b = row >> 14, s = row & (SEQ - 1);
;                         *(u32x4*)(base + (size_t)b * bstride + (size_t)s * 128 + d) = pack8v(v0, v1);
;                     } else if (kind == 1) {
; #pragma unroll
;                         for (int e = 0; e < 4; ++e) { v0[e] = sigmoidf_(v0[e]); v1[e] = sigmoidf_(v1[e]); }
;                         __builtin_nontemporal_store(pack8v(v0, v1), (u32x4*)(base + (size_t)row * 4096 + d));
;                     } else {
;                         if (d < 24) { float* gn = (float*)(ws + WS_GN) + (size_t)row * 24 + d;
; #pragma unroll
;                             for (int e = 0; e < 4; ++e) { v0[e] = sigmoidf_(v0[e]); v1[e] = sigmoidf_(v1[e]); }
;                             *(f32x4*)gn = v0; *(f32x4*)(gn + 4) = v1; }
.LBB0_324:
	v_cvt_pk_bf16_f32 v92, v92, v93
	v_cvt_pk_bf16_f32 v93, v94, v95
	v_cvt_pk_bf16_f32 v94, v88, v89
	v_lshlrev_b32_e32 v88, 8, v96
	v_and_b32_e32 v136, 0x3fcf00, v88
	v_lshl_add_u64 v[88:89], v[154:155], 0, v[136:137]
	v_cvt_pk_bf16_f32 v95, v90, v91
	global_store_dwordx4 v[88:89], v[92:95], off nt
	v_or_b32_e32 v88, 0x90, v150
	s_and_b64 vcc, exec, s[10:11]
	s_mov_b64 s[58:59], -1
	s_cbranch_vccnz .LBB0_219
.LBB0_325:
	s_and_b64 vcc, exec, s[8:9]
	s_cbranch_vccnz .LBB0_329
	s_and_saveexec_b64 s[58:59], s[4:5]
	s_cbranch_execz .LBB0_328
	v_mul_f32_e32 v89, 0xbfb8aa3b, v84
	v_exp_f32_e32 v89, v89
	v_mul_f32_e32 v90, 0xbfb8aa3b, v80
	v_exp_f32_e32 v90, v90
	v_mul_f32_e32 v92, 0xbfb8aa3b, v81
	v_add_f32_e32 v89, 1.0, v89
	v_exp_f32_e32 v92, v92
	v_add_f32_e32 v91, 1.0, v90
	v_rcp_f32_e32 v90, v89
	v_mul_f32_e32 v89, 0xbfb8aa3b, v85
	v_exp_f32_e32 v89, v89
	v_rcp_f32_e32 v94, v91
	v_mul_f32_e32 v93, 0xbfb8aa3b, v82
	v_exp_f32_e32 v93, v93
	v_add_f32_e32 v89, 1.0, v89
	v_rcp_f32_e32 v91, v89
	v_add_f32_e32 v89, 1.0, v92
	v_mul_f32_e32 v92, 0xbfb8aa3b, v86
	v_exp_f32_e32 v92, v92
	v_rcp_f32_e32 v95, v89
	v_mul_f32_e32 v96, 0xbfb8aa3b, v83
	v_exp_f32_e32 v97, v96
	v_add_f32_e32 v89, 1.0, v92
	v_rcp_f32_e32 v92, v89
	v_add_f32_e32 v89, 1.0, v93
	v_mul_f32_e32 v93, 0xbfb8aa3b, v87
	v_exp_f32_e32 v93, v93
	v_rcp_f32_e32 v96, v89
	v_mad_i64_i32 v[98:99], s[20:21], v88, s27, v[140:141]
	v_add_f32_e32 v89, 1.0, v93
	v_rcp_f32_e32 v93, v89
	v_add_f32_e32 v89, 1.0, v97
	v_rcp_f32_e32 v97, v89
	global_store_dwordx4 v[98:99], v[90:93], off nt
	global_store_dwordx4 v[98:99], v[94:97], off offset:16 nt

; __device__ __forceinline__ float sigmoidf_(float x) { return __builtin_amdgcn_rcpf(1.f + __builtin_amdgcn_exp2f(-1.4426950408889634f * x)); }
; __device__ __forceinline__ u32x4 pack8v(f32x4 a, f32x4 b) { u32x4 w; w.x = cvtpk(a[0], a[1]); w.y = cvtpk(a[2], a[3]); w.z = cvtpk(b[0], b[1]); w.w = cvtpk(b[2], b[3]); return w; }
;     __device__ __forceinline__ void operator()(const Acc& acc, const Unit& u, int wr, int wc, int fr, int fq) const {
;     ...
;                     if (kind == 0) {
;                         const int b = row >> 14, s = row & (SEQ - 1);
;                         *(u32x4*)(base + (size_t)b * bstride + (size_t)s * 128 + d) = pack8v(v0, v1);
;                     } else if (kind == 1) {
; #pragma unroll
;                         for (int e = 0; e < 4; ++e) { v0[e] = sigmoidf_(v0[e]); v1[e] = sigmoidf_(v1[e]); }
;                         __builtin_nontemporal_store(pack8v(v0, v1), (u32x4*)(base + (size_t)row * 4096 + d));
;                     } else {
;                         if (d < 24) { float* gn = (float*)(ws + WS_GN) + (size_t)row * 24 + d;
; #pragma unroll
;                             for (int e = 0; e < 4; ++e) { v0[e] = sigmoidf_(v0[e]); v1[e] = sigmoidf_(v1[e]); }
;                             *(f32x4*)gn = v0; *(f32x4*)(gn + 4) = v1; }
.LBB0_332:
	v_cvt_pk_bf16_f32 v84, v84, v85
	v_cvt_pk_bf16_f32 v85, v86, v87
	v_cvt_pk_bf16_f32 v86, v80, v81
	v_lshlrev_b32_e32 v80, 8, v88
	v_and_b32_e32 v136, 0x3fdf00, v80
	v_lshl_add_u64 v[80:81], v[154:155], 0, v[136:137]
	v_cvt_pk_bf16_f32 v87, v82, v83
	global_store_dwordx4 v[80:81], v[84:87], off nt
	v_or_b32_e32 v80, 0xa0, v150
	s_and_b64 vcc, exec, s[10:11]
	s_mov_b64 s[58:59], -1
	s_cbranch_vccnz .LBB0_221
.LBB0_333:
	s_and_b64 vcc, exec, s[8:9]
	s_cbranch_vccnz .LBB0_337
	s_and_saveexec_b64 s[58:59], s[4:5]
	s_cbranch_execz .LBB0_336
	v_mul_f32_e32 v81, 0xbfb8aa3b, v76
	v_exp_f32_e32 v81, v81
	v_mul_f32_e32 v82, 0xbfb8aa3b, v72
	v_exp_f32_e32 v82, v82
	v_mul_f32_e32 v84, 0xbfb8aa3b, v73
	v_add_f32_e32 v81, 1.0, v81
	v_exp_f32_e32 v84, v84
	v_add_f32_e32 v83, 1.0, v82
	v_rcp_f32_e32 v82, v81
	v_mul_f32_e32 v81, 0xbfb8aa3b, v77
	v_exp_f32_e32 v81, v81
	v_rcp_f32_e32 v86, v83
	v_mul_f32_e32 v85, 0xbfb8aa3b, v74
	v_exp_f32_e32 v85, v85
	v_add_f32_e32 v81, 1.0, v81
	v_rcp_f32_e32 v83, v81
	v_add_f32_e32 v81, 1.0, v84
	v_mul_f32_e32 v84, 0xbfb8aa3b, v78
	v_exp_f32_e32 v84, v84
	v_rcp_f32_e32 v87, v81
	v_mul_f32_e32 v88, 0xbfb8aa3b, v75
	v_exp_f32_e32 v89, v88
	v_add_f32_e32 v81, 1.0, v84
	v_rcp_f32_e32 v84, v81
	v_add_f32_e32 v81, 1.0, v85
	v_mul_f32_e32 v85, 0xbfb8aa3b, v79
	v_exp_f32_e32 v85, v85
	v_rcp_f32_e32 v88, v81
	v_mad_i64_i32 v[90:91], s[20:21], v80, s27, v[140:141]
	v_add_f32_e32 v81, 1.0, v85
	v_rcp_f32_e32 v85, v81
	v_add_f32_e32 v81, 1.0, v89
	v_rcp_f32_e32 v89, v81
	global_store_dwordx4 v[90:91], v[82:85], off nt
	global_store_dwordx4 v[90:91], v[86:89], off offset:16 nt

; __device__ __forceinline__ float sigmoidf_(float x) { return __builtin_amdgcn_rcpf(1.f + __builtin_amdgcn_exp2f(-1.4426950408889634f * x)); }
; __device__ __forceinline__ u32x4 pack8v(f32x4 a, f32x4 b) { u32x4 w; w.x = cvtpk(a[0], a[1]); w.y = cvtpk(a[2], a[3]); w.z = cvtpk(b[0], b[1]); w.w = cvtpk(b[2], b[3]); return w; }
;     __device__ __forceinline__ void operator()(const Acc& acc, const Unit& u, int wr, int wc, int fr, int fq) const {
;     ...
;                     if (kind == 0) {
;                         const int b = row >> 14, s = row & (SEQ - 1);
;                         *(u32x4*)(base + (size_t)b * bstride + (size_t)s * 128 + d) = pack8v(v0, v1);
;                     } else if (kind == 1) {
; #pragma unroll
;                         for (int e = 0; e < 4; ++e) { v0[e] = sigmoidf_(v0[e]); v1[e] = sigmoidf_(v1[e]); }
;                         __builtin_nontemporal_store(pack8v(v0, v1), (u32x4*)(base + (size_t)row * 4096 + d));
;                     } else {
;                         if (d < 24) { float* gn = (float*)(ws + WS_GN) + (size_t)row * 24 + d;
; #pragma unroll
;                             for (int e = 0; e < 4; ++e) { v0[e] = sigmoidf_(v0[e]); v1[e] = sigmoidf_(v1[e]); }
;                             *(f32x4*)gn = v0; *(f32x4*)(gn + 4) = v1; }
.LBB0_340:
	v_cvt_pk_bf16_f32 v76, v76, v77
	v_cvt_pk_bf16_f32 v77, v78, v79
	v_cvt_pk_bf16_f32 v78, v72, v73
	v_lshlrev_b32_e32 v72, 8, v80
	v_and_b32_e32 v136, 0x3fef00, v72
	v_lshl_add_u64 v[72:73], v[154:155], 0, v[136:137]
	v_cvt_pk_bf16_f32 v79, v74, v75
	global_store_dwordx4 v[72:73], v[76:79], off nt
	v_or_b32_e32 v72, 0xb0, v150
	s_and_b64 vcc, exec, s[10:11]
	s_mov_b64 s[10:11], -1
	s_cbranch_vccnz .LBB0_223
.LBB0_341:
	s_and_b64 vcc, exec, s[8:9]
	s_mov_b64 s[8:9], -1
	s_cbranch_vccnz .LBB0_345
	s_and_saveexec_b64 s[8:9], s[4:5]
	s_cbranch_execz .LBB0_344
	v_mul_f32_e32 v73, 0xbfb8aa3b, v68
	v_exp_f32_e32 v73, v73
	v_mul_f32_e32 v74, 0xbfb8aa3b, v64
	v_exp_f32_e32 v74, v74
	v_mul_f32_e32 v76, 0xbfb8aa3b, v65
	v_add_f32_e32 v73, 1.0, v73
	v_exp_f32_e32 v76, v76
	v_add_f32_e32 v75, 1.0, v74
	v_rcp_f32_e32 v74, v73
	v_mul_f32_e32 v73, 0xbfb8aa3b, v69
	v_exp_f32_e32 v73, v73
	v_rcp_f32_e32 v78, v75
	v_mul_f32_e32 v77, 0xbfb8aa3b, v66
	v_exp_f32_e32 v77, v77
	v_add_f32_e32 v73, 1.0, v73
	v_rcp_f32_e32 v75, v73
	v_add_f32_e32 v73, 1.0, v76
	v_mul_f32_e32 v76, 0xbfb8aa3b, v70
	v_exp_f32_e32 v76, v76
	v_rcp_f32_e32 v79, v73
	v_mul_f32_e32 v80, 0xbfb8aa3b, v67
	v_exp_f32_e32 v81, v80
	v_add_f32_e32 v73, 1.0, v76
	v_rcp_f32_e32 v76, v73
	v_add_f32_e32 v73, 1.0, v77
	v_mul_f32_e32 v77, 0xbfb8aa3b, v71
	v_exp_f32_e32 v77, v77
	v_rcp_f32_e32 v80, v73
	v_mad_i64_i32 v[82:83], s[10:11], v72, s27, v[140:141]
	v_add_f32_e32 v73, 1.0, v77
	v_rcp_f32_e32 v77, v73
	v_add_f32_e32 v73, 1.0, v81
	v_rcp_f32_e32 v81, v73
	global_store_dwordx4 v[82:83], v[74:77], off nt
	global_store_dwordx4 v[82:83], v[78:81], off offset:16 nt

; __device__ __forceinline__ float sigmoidf_(float x) { return __builtin_amdgcn_rcpf(1.f + __builtin_amdgcn_exp2f(-1.4426950408889634f * x)); }
;     __device__ __forceinline__ void operator()(const Acc& acc, const Unit& u, int wr, int wc, int fr, int fq) const {
;     ...
;                         if (d < 24) { float* gn = (float*)(ws + WS_GN) + (size_t)row * 24 + d;
; #pragma unroll
;                             for (int e = 0; e < 4; ++e) { v0[e] = sigmoidf_(v0[e]); v1[e] = sigmoidf_(v1[e]); }
;                             *(f32x4*)gn = v0; *(f32x4*)(gn + 4) = v1; }
.LBB0_348:
	s_and_b64 vcc, exec, s[8:9]
	s_cbranch_vccnz .LBB0_352
	s_and_saveexec_b64 s[54:55], s[4:5]
	s_cbranch_execz .LBB0_351
	v_mul_f32_e32 v57, 0xbfb8aa3b, v52
	v_exp_f32_e32 v57, v57
	v_mul_f32_e32 v58, 0xbfb8aa3b, v48
	v_exp_f32_e32 v58, v58
	v_mul_f32_e32 v60, 0xbfb8aa3b, v49
	v_add_f32_e32 v57, 1.0, v57
	v_exp_f32_e32 v60, v60
	v_add_f32_e32 v59, 1.0, v58
	v_rcp_f32_e32 v58, v57
	v_mul_f32_e32 v57, 0xbfb8aa3b, v53
	v_exp_f32_e32 v57, v57
	v_rcp_f32_e32 v68, v59
	v_mul_f32_e32 v61, 0xbfb8aa3b, v50
	v_exp_f32_e32 v61, v61
	v_add_f32_e32 v57, 1.0, v57
	v_rcp_f32_e32 v59, v57
	v_add_f32_e32 v57, 1.0, v60
	v_mul_f32_e32 v60, 0xbfb8aa3b, v54
	v_exp_f32_e32 v60, v60
	v_rcp_f32_e32 v69, v57
	v_mul_f32_e32 v62, 0xbfb8aa3b, v51
	v_exp_f32_e32 v62, v62
	v_add_f32_e32 v57, 1.0, v60
	v_rcp_f32_e32 v60, v57
	v_add_f32_e32 v57, 1.0, v61
	v_mul_f32_e32 v61, 0xbfb8aa3b, v55
	v_exp_f32_e32 v61, v61
	v_rcp_f32_e32 v70, v57
	v_add_f32_e32 v57, 1.0, v61
	v_rcp_f32_e32 v61, v57
	v_add_f32_e32 v57, 1.0, v62
	v_rcp_f32_e32 v71, v57
	v_mad_i64_i32 v[62:63], s[20:21], v56, s27, v[140:141]
	global_store_dwordx4 v[62:63], v[58:61], off nt
	global_store_dwordx4 v[62:63], v[68:71], off offset:16 nt

; __device__ __forceinline__ float sigmoidf_(float x) { return __builtin_amdgcn_rcpf(1.f + __builtin_amdgcn_exp2f(-1.4426950408889634f * x)); }
; __device__ __forceinline__ u32x4 pack8v(f32x4 a, f32x4 b) { u32x4 w; w.x = cvtpk(a[0], a[1]); w.y = cvtpk(a[2], a[3]); w.z = cvtpk(b[0], b[1]); w.w = cvtpk(b[2], b[3]); return w; }
;     __device__ __forceinline__ void operator()(const Acc& acc, const Unit& u, int wr, int wc, int fr, int fq) const {
;     ...
;                     if (kind == 0) {
;                         const int b = row >> 14, s = row & (SEQ - 1);
;                         *(u32x4*)(base + (size_t)b * bstride + (size_t)s * 128 + d) = pack8v(v0, v1);
;                     } else if (kind == 1) {
; #pragma unroll
;                         for (int e = 0; e < 4; ++e) { v0[e] = sigmoidf_(v0[e]); v1[e] = sigmoidf_(v1[e]); }
;                         __builtin_nontemporal_store(pack8v(v0, v1), (u32x4*)(base + (size_t)row * 4096 + d));
;                     } else {
;                         if (d < 24) { float* gn = (float*)(ws + WS_GN) + (size_t)row * 24 + d;
; #pragma unroll
;                             for (int e = 0; e < 4; ++e) { v0[e] = sigmoidf_(v0[e]); v1[e] = sigmoidf_(v1[e]); }
;                             *(f32x4*)gn = v0; *(f32x4*)(gn + 4) = v1; }
.LBB0_355:
	v_cvt_pk_bf16_f32 v52, v52, v53
	v_cvt_pk_bf16_f32 v53, v54, v55
	v_cvt_pk_bf16_f32 v54, v48, v49
	v_lshlrev_b32_e32 v48, 8, v56
	v_and_b32_e32 v136, 0x3f5f00, v48
	v_lshl_add_u64 v[48:49], v[66:67], 0, v[136:137]
	v_cvt_pk_bf16_f32 v55, v50, v51
	global_store_dwordx4 v[48:49], v[52:55], off nt
	v_or_b32_e32 v48, 32, v150
	s_and_b64 vcc, exec, s[10:11]
	s_mov_b64 s[54:55], -1
	s_cbranch_vccnz .LBB0_278
.LBB0_356:
	s_and_b64 vcc, exec, s[8:9]
	s_cbranch_vccnz .LBB0_360
	s_and_saveexec_b64 s[54:55], s[4:5]
	s_cbranch_execz .LBB0_359
	v_mul_f32_e32 v49, 0xbfb8aa3b, v44
	v_exp_f32_e32 v49, v49
	v_mul_f32_e32 v50, 0xbfb8aa3b, v40
	v_exp_f32_e32 v50, v50
	v_mul_f32_e32 v52, 0xbfb8aa3b, v41
	v_add_f32_e32 v49, 1.0, v49
	v_exp_f32_e32 v52, v52
	v_add_f32_e32 v51, 1.0, v50
	v_rcp_f32_e32 v50, v49
	v_mul_f32_e32 v49, 0xbfb8aa3b, v45
	v_exp_f32_e32 v49, v49
	v_rcp_f32_e32 v54, v51
	v_mul_f32_e32 v53, 0xbfb8aa3b, v42
	v_exp_f32_e32 v53, v53
	v_add_f32_e32 v49, 1.0, v49
	v_rcp_f32_e32 v51, v49
	v_add_f32_e32 v49, 1.0, v52
	v_mul_f32_e32 v52, 0xbfb8aa3b, v46
	v_exp_f32_e32 v52, v52
	v_rcp_f32_e32 v55, v49
	v_mul_f32_e32 v56, 0xbfb8aa3b, v43
	v_exp_f32_e32 v57, v56
	v_add_f32_e32 v49, 1.0, v52
	v_rcp_f32_e32 v52, v49
	v_add_f32_e32 v49, 1.0, v53
	v_mul_f32_e32 v53, 0xbfb8aa3b, v47
	v_exp_f32_e32 v53, v53
	v_rcp_f32_e32 v56, v49
	v_mad_i64_i32 v[58:59], s[20:21], v48, s27, v[140:141]
	v_add_f32_e32 v49, 1.0, v53
	v_rcp_f32_e32 v53, v49
	v_add_f32_e32 v49, 1.0, v57
	v_rcp_f32_e32 v57, v49
	global_store_dwordx4 v[58:59], v[50:53], off nt
	global_store_dwordx4 v[58:59], v[54:57], off offset:16 nt

; __device__ __forceinline__ float sigmoidf_(float x) { return __builtin_amdgcn_rcpf(1.f + __builtin_amdgcn_exp2f(-1.4426950408889634f * x)); }
; __device__ __forceinline__ u32x4 pack8v(f32x4 a, f32x4 b) { u32x4 w; w.x = cvtpk(a[0], a[1]); w.y = cvtpk(a[2], a[3]); w.z = cvtpk(b[0], b[1]); w.w = cvtpk(b[2], b[3]); return w; }
;     __device__ __forceinline__ void operator()(const Acc& acc, const Unit& u, int wr, int wc, int fr, int fq) const {
;     ...
;                     if (kind == 0) {
;                         const int b = row >> 14, s = row & (SEQ - 1);
;                         *(u32x4*)(base + (size_t)b * bstride + (size_t)s * 128 + d) = pack8v(v0, v1);
;                     } else if (kind == 1) {
; #pragma unroll
;                         for (int e = 0; e < 4; ++e) { v0[e] = sigmoidf_(v0[e]); v1[e] = sigmoidf_(v1[e]); }
;                         __builtin_nontemporal_store(pack8v(v0, v1), (u32x4*)(base + (size_t)row * 4096 + d));
;                     } else {
;                         if (d < 24) { float* gn = (float*)(ws + WS_GN) + (size_t)row * 24 + d;
; #pragma unroll
;                             for (int e = 0; e < 4; ++e) { v0[e] = sigmoidf_(v0[e]); v1[e] = sigmoidf_(v1[e]); }
;                             *(f32x4*)gn = v0; *(f32x4*)(gn + 4) = v1; }
.LBB0_363:
	v_cvt_pk_bf16_f32 v44, v44, v45
	v_cvt_pk_bf16_f32 v45, v46, v47
	v_cvt_pk_bf16_f32 v46, v40, v41
	v_lshlrev_b32_e32 v40, 8, v48
	v_and_b32_e32 v136, 0x3f6f00, v40
	v_lshl_add_u64 v[40:41], v[66:67], 0, v[136:137]
	v_cvt_pk_bf16_f32 v47, v42, v43
	global_store_dwordx4 v[40:41], v[44:47], off nt
	v_or_b32_e32 v40, 48, v150
	s_and_b64 vcc, exec, s[10:11]
	s_mov_b64 s[54:55], -1
	s_cbranch_vccnz .LBB0_280
.LBB0_364:
	s_and_b64 vcc, exec, s[8:9]
	s_cbranch_vccnz .LBB0_368
	s_and_saveexec_b64 s[54:55], s[4:5]
	s_cbranch_execz .LBB0_367
	v_mul_f32_e32 v41, 0xbfb8aa3b, v36
	v_exp_f32_e32 v41, v41
	v_mul_f32_e32 v42, 0xbfb8aa3b, v32
	v_exp_f32_e32 v42, v42
	v_mul_f32_e32 v44, 0xbfb8aa3b, v33
	v_add_f32_e32 v41, 1.0, v41
	v_exp_f32_e32 v44, v44
	v_add_f32_e32 v43, 1.0, v42
	v_rcp_f32_e32 v42, v41
	v_mul_f32_e32 v41, 0xbfb8aa3b, v37
	v_exp_f32_e32 v41, v41
	v_rcp_f32_e32 v46, v43
	v_mul_f32_e32 v45, 0xbfb8aa3b, v34
	v_exp_f32_e32 v45, v45
	v_add_f32_e32 v41, 1.0, v41
	v_rcp_f32_e32 v43, v41
	v_add_f32_e32 v41, 1.0, v44
	v_mul_f32_e32 v44, 0xbfb8aa3b, v38
	v_exp_f32_e32 v44, v44
	v_rcp_f32_e32 v47, v41
	v_mul_f32_e32 v48, 0xbfb8aa3b, v35
	v_exp_f32_e32 v49, v48
	v_add_f32_e32 v41, 1.0, v44
	v_rcp_f32_e32 v44, v41
	v_add_f32_e32 v41, 1.0, v45
	v_mul_f32_e32 v45, 0xbfb8aa3b, v39
	v_exp_f32_e32 v45, v45
	v_rcp_f32_e32 v48, v41
	v_mad_i64_i32 v[50:51], s[20:21], v40, s27, v[140:141]
	v_add_f32_e32 v41, 1.0, v45
	v_rcp_f32_e32 v45, v41
	v_add_f32_e32 v41, 1.0, v49
	v_rcp_f32_e32 v49, v41
	global_store_dwordx4 v[50:51], v[42:45], off nt
	global_store_dwordx4 v[50:51], v[46:49], off offset:16 nt

; __device__ __forceinline__ float sigmoidf_(float x) { return __builtin_amdgcn_rcpf(1.f + __builtin_amdgcn_exp2f(-1.4426950408889634f * x)); }
; __device__ __forceinline__ u32x4 pack8v(f32x4 a, f32x4 b) { u32x4 w; w.x = cvtpk(a[0], a[1]); w.y = cvtpk(a[2], a[3]); w.z = cvtpk(b[0], b[1]); w.w = cvtpk(b[2], b[3]); return w; }
;     __device__ __forceinline__ void operator()(const Acc& acc, const Unit& u, int wr, int wc, int fr, int fq) const {
;     ...
;                     if (kind == 0) {
;                         const int b = row >> 14, s = row & (SEQ - 1);
;                         *(u32x4*)(base + (size_t)b * bstride + (size_t)s * 128 + d) = pack8v(v0, v1);
;                     } else if (kind == 1) {
; #pragma unroll
;                         for (int e = 0; e < 4; ++e) { v0[e] = sigmoidf_(v0[e]); v1[e] = sigmoidf_(v1[e]); }
;                         __builtin_nontemporal_store(pack8v(v0, v1), (u32x4*)(base + (size_t)row * 4096 + d));
;                     } else {
;                         if (d < 24) { float* gn = (float*)(ws + WS_GN) + (size_t)row * 24 + d;
; #pragma unroll
;                             for (int e = 0; e < 4; ++e) { v0[e] = sigmoidf_(v0[e]); v1[e] = sigmoidf_(v1[e]); }
;                             *(f32x4*)gn = v0; *(f32x4*)(gn + 4) = v1; }
.LBB0_371:
	v_cvt_pk_bf16_f32 v36, v36, v37
	v_cvt_pk_bf16_f32 v37, v38, v39
	v_cvt_pk_bf16_f32 v38, v32, v33
	v_lshlrev_b32_e32 v32, 8, v40
	v_and_b32_e32 v136, 0x3f7f00, v32
	v_lshl_add_u64 v[32:33], v[66:67], 0, v[136:137]
	v_cvt_pk_bf16_f32 v39, v34, v35
	global_store_dwordx4 v[32:33], v[36:39], off nt
	v_or_b32_e32 v32, 0x80, v150
	s_and_b64 vcc, exec, s[10:11]
	s_mov_b64 s[54:55], -1
	s_cbranch_vccnz .LBB0_282
.LBB0_372:
	s_and_b64 vcc, exec, s[8:9]
	s_cbranch_vccnz .LBB0_376
	s_and_saveexec_b64 s[54:55], s[4:5]
	s_cbranch_execz .LBB0_375
	v_mul_f32_e32 v33, 0xbfb8aa3b, v28
	v_exp_f32_e32 v33, v33
	v_mul_f32_e32 v34, 0xbfb8aa3b, v24
	v_exp_f32_e32 v34, v34
	v_mul_f32_e32 v36, 0xbfb8aa3b, v25
	v_add_f32_e32 v33, 1.0, v33
	v_exp_f32_e32 v36, v36
	v_add_f32_e32 v35, 1.0, v34
	v_rcp_f32_e32 v34, v33
	v_mul_f32_e32 v33, 0xbfb8aa3b, v29
	v_exp_f32_e32 v33, v33
	v_rcp_f32_e32 v38, v35
	v_mul_f32_e32 v37, 0xbfb8aa3b, v26
	v_exp_f32_e32 v37, v37
	v_add_f32_e32 v33, 1.0, v33
	v_rcp_f32_e32 v35, v33
	v_add_f32_e32 v33, 1.0, v36
	v_mul_f32_e32 v36, 0xbfb8aa3b, v30
	v_exp_f32_e32 v36, v36
	v_rcp_f32_e32 v39, v33
	v_mul_f32_e32 v40, 0xbfb8aa3b, v27
	v_exp_f32_e32 v41, v40
	v_add_f32_e32 v33, 1.0, v36
	v_rcp_f32_e32 v36, v33
	v_add_f32_e32 v33, 1.0, v37
	v_mul_f32_e32 v37, 0xbfb8aa3b, v31
	v_exp_f32_e32 v37, v37
	v_rcp_f32_e32 v40, v33
	v_mad_i64_i32 v[42:43], s[20:21], v32, s27, v[140:141]
	v_add_f32_e32 v33, 1.0, v37
	v_rcp_f32_e32 v37, v33
	v_add_f32_e32 v33, 1.0, v41
	v_rcp_f32_e32 v41, v33
	global_store_dwordx4 v[42:43], v[34:37], off nt
	global_store_dwordx4 v[42:43], v[38:41], off offset:16 nt

; __device__ __forceinline__ float sigmoidf_(float x) { return __builtin_amdgcn_rcpf(1.f + __builtin_amdgcn_exp2f(-1.4426950408889634f * x)); }
; __device__ __forceinline__ u32x4 pack8v(f32x4 a, f32x4 b) { u32x4 w; w.x = cvtpk(a[0], a[1]); w.y = cvtpk(a[2], a[3]); w.z = cvtpk(b[0], b[1]); w.w = cvtpk(b[2], b[3]); return w; }
;     __device__ __forceinline__ void operator()(const Acc& acc, const Unit& u, int wr, int wc, int fr, int fq) const {
;     ...
;                     if (kind == 0) {
;                         const int b = row >> 14, s = row & (SEQ - 1);
;                         *(u32x4*)(base + (size_t)b * bstride + (size_t)s * 128 + d) = pack8v(v0, v1);
;                     } else if (kind == 1) {
; #pragma unroll
;                         for (int e = 0; e < 4; ++e) { v0[e] = sigmoidf_(v0[e]); v1[e] = sigmoidf_(v1[e]); }
;                         __builtin_nontemporal_store(pack8v(v0, v1), (u32x4*)(base + (size_t)row * 4096 + d));
;                     } else {
;                         if (d < 24) { float* gn = (float*)(ws + WS_GN) + (size_t)row * 24 + d;
; #pragma unroll
;                             for (int e = 0; e < 4; ++e) { v0[e] = sigmoidf_(v0[e]); v1[e] = sigmoidf_(v1[e]); }
;                             *(f32x4*)gn = v0; *(f32x4*)(gn + 4) = v1; }
.LBB0_379:
	v_cvt_pk_bf16_f32 v28, v28, v29
	v_cvt_pk_bf16_f32 v29, v30, v31
	v_cvt_pk_bf16_f32 v30, v24, v25
	v_lshlrev_b32_e32 v24, 8, v32
	v_and_b32_e32 v136, 0x3fcf00, v24
	v_lshl_add_u64 v[24:25], v[66:67], 0, v[136:137]
	v_cvt_pk_bf16_f32 v31, v26, v27
	global_store_dwordx4 v[24:25], v[28:31], off nt
	v_or_b32_e32 v24, 0x90, v150
	s_and_b64 vcc, exec, s[10:11]
	s_mov_b64 s[54:55], -1
	s_cbranch_vccnz .LBB0_284
.LBB0_380:
	s_and_b64 vcc, exec, s[8:9]
	s_cbranch_vccnz .LBB0_384
	s_and_saveexec_b64 s[54:55], s[4:5]
	s_cbranch_execz .LBB0_383
	v_mul_f32_e32 v25, 0xbfb8aa3b, v20
	v_exp_f32_e32 v25, v25
	v_mul_f32_e32 v26, 0xbfb8aa3b, v16
	v_exp_f32_e32 v26, v26
	v_mul_f32_e32 v28, 0xbfb8aa3b, v17
	v_add_f32_e32 v25, 1.0, v25
	v_exp_f32_e32 v28, v28
	v_add_f32_e32 v27, 1.0, v26
	v_rcp_f32_e32 v26, v25
	v_mul_f32_e32 v25, 0xbfb8aa3b, v21
	v_exp_f32_e32 v25, v25
	v_rcp_f32_e32 v30, v27
	v_mul_f32_e32 v29, 0xbfb8aa3b, v18
	v_exp_f32_e32 v29, v29
	v_add_f32_e32 v25, 1.0, v25
	v_rcp_f32_e32 v27, v25
	v_add_f32_e32 v25, 1.0, v28
	v_mul_f32_e32 v28, 0xbfb8aa3b, v22
	v_exp_f32_e32 v28, v28
	v_rcp_f32_e32 v31, v25
	v_mul_f32_e32 v32, 0xbfb8aa3b, v19
	v_exp_f32_e32 v33, v32
	v_add_f32_e32 v25, 1.0, v28
	v_rcp_f32_e32 v28, v25
	v_add_f32_e32 v25, 1.0, v29
	v_mul_f32_e32 v29, 0xbfb8aa3b, v23
	v_exp_f32_e32 v29, v29
	v_rcp_f32_e32 v32, v25
	v_mad_i64_i32 v[34:35], s[20:21], v24, s27, v[140:141]
	v_add_f32_e32 v25, 1.0, v29
	v_rcp_f32_e32 v29, v25
	v_add_f32_e32 v25, 1.0, v33
	v_rcp_f32_e32 v33, v25
	global_store_dwordx4 v[34:35], v[26:29], off nt
	global_store_dwordx4 v[34:35], v[30:33], off offset:16 nt

; __device__ __forceinline__ float sigmoidf_(float x) { return __builtin_amdgcn_rcpf(1.f + __builtin_amdgcn_exp2f(-1.4426950408889634f * x)); }
; __device__ __forceinline__ u32x4 pack8v(f32x4 a, f32x4 b) { u32x4 w; w.x = cvtpk(a[0], a[1]); w.y = cvtpk(a[2], a[3]); w.z = cvtpk(b[0], b[1]); w.w = cvtpk(b[2], b[3]); return w; }
;     __device__ __forceinline__ void operator()(const Acc& acc, const Unit& u, int wr, int wc, int fr, int fq) const {
;     ...
;                     if (kind == 0) {
;                         const int b = row >> 14, s = row & (SEQ - 1);
;                         *(u32x4*)(base + (size_t)b * bstride + (size_t)s * 128 + d) = pack8v(v0, v1);
;                     } else if (kind == 1) {
; #pragma unroll
;                         for (int e = 0; e < 4; ++e) { v0[e] = sigmoidf_(v0[e]); v1[e] = sigmoidf_(v1[e]); }
;                         __builtin_nontemporal_store(pack8v(v0, v1), (u32x4*)(base + (size_t)row * 4096 + d));
;                     } else {
;                         if (d < 24) { float* gn = (float*)(ws + WS_GN) + (size_t)row * 24 + d;
; #pragma unroll
;                             for (int e = 0; e < 4; ++e) { v0[e] = sigmoidf_(v0[e]); v1[e] = sigmoidf_(v1[e]); }
;                             *(f32x4*)gn = v0; *(f32x4*)(gn + 4) = v1; }
.LBB0_387:
	v_cvt_pk_bf16_f32 v20, v20, v21
	v_cvt_pk_bf16_f32 v21, v22, v23
	v_cvt_pk_bf16_f32 v22, v16, v17
	v_lshlrev_b32_e32 v16, 8, v24
	v_and_b32_e32 v136, 0x3fdf00, v16
	v_lshl_add_u64 v[16:17], v[66:67], 0, v[136:137]
	v_cvt_pk_bf16_f32 v23, v18, v19
	global_store_dwordx4 v[16:17], v[20:23], off nt
	v_or_b32_e32 v16, 0xa0, v150
	s_and_b64 vcc, exec, s[10:11]
	s_mov_b64 s[54:55], -1
	s_cbranch_vccnz .LBB0_286
.LBB0_388:
	s_and_b64 vcc, exec, s[8:9]
	s_cbranch_vccnz .LBB0_392
	s_and_saveexec_b64 s[54:55], s[4:5]
	s_cbranch_execz .LBB0_391
	v_mul_f32_e32 v17, 0xbfb8aa3b, v12
	v_exp_f32_e32 v17, v17
	v_mul_f32_e32 v18, 0xbfb8aa3b, v8
	v_exp_f32_e32 v18, v18
	v_mul_f32_e32 v20, 0xbfb8aa3b, v9
	v_add_f32_e32 v17, 1.0, v17
	v_exp_f32_e32 v20, v20
	v_add_f32_e32 v19, 1.0, v18
	v_rcp_f32_e32 v18, v17
	v_mul_f32_e32 v17, 0xbfb8aa3b, v13
	v_exp_f32_e32 v17, v17
	v_rcp_f32_e32 v22, v19
	v_mul_f32_e32 v21, 0xbfb8aa3b, v10
	v_exp_f32_e32 v21, v21
	v_add_f32_e32 v17, 1.0, v17
	v_rcp_f32_e32 v19, v17
	v_add_f32_e32 v17, 1.0, v20
	v_mul_f32_e32 v20, 0xbfb8aa3b, v14
	v_exp_f32_e32 v20, v20
	v_rcp_f32_e32 v23, v17
	v_mul_f32_e32 v24, 0xbfb8aa3b, v11
	v_exp_f32_e32 v25, v24
	v_add_f32_e32 v17, 1.0, v20
	v_rcp_f32_e32 v20, v17
	v_add_f32_e32 v17, 1.0, v21
	v_mul_f32_e32 v21, 0xbfb8aa3b, v15
	v_exp_f32_e32 v21, v21
	v_rcp_f32_e32 v24, v17
	v_mad_i64_i32 v[26:27], s[20:21], v16, s27, v[140:141]
	v_add_f32_e32 v17, 1.0, v21
	v_rcp_f32_e32 v21, v17
	v_add_f32_e32 v17, 1.0, v25
	v_rcp_f32_e32 v25, v17
	global_store_dwordx4 v[26:27], v[18:21], off nt
	global_store_dwordx4 v[26:27], v[22:25], off offset:16 nt

; __device__ __forceinline__ float sigmoidf_(float x) { return __builtin_amdgcn_rcpf(1.f + __builtin_amdgcn_exp2f(-1.4426950408889634f * x)); }
; __device__ __forceinline__ u32x4 pack8v(f32x4 a, f32x4 b) { u32x4 w; w.x = cvtpk(a[0], a[1]); w.y = cvtpk(a[2], a[3]); w.z = cvtpk(b[0], b[1]); w.w = cvtpk(b[2], b[3]); return w; }
;     __device__ __forceinline__ void operator()(const Acc& acc, const Unit& u, int wr, int wc, int fr, int fq) const {
;     ...
;                     if (kind == 0) {
;                         const int b = row >> 14, s = row & (SEQ - 1);
;                         *(u32x4*)(base + (size_t)b * bstride + (size_t)s * 128 + d) = pack8v(v0, v1);
;                     } else if (kind == 1) {
; #pragma unroll
;                         for (int e = 0; e < 4; ++e) { v0[e] = sigmoidf_(v0[e]); v1[e] = sigmoidf_(v1[e]); }
;                         __builtin_nontemporal_store(pack8v(v0, v1), (u32x4*)(base + (size_t)row * 4096 + d));
;                     } else {
;                         if (d < 24) { float* gn = (float*)(ws + WS_GN) + (size_t)row * 24 + d;
; #pragma unroll
;                             for (int e = 0; e < 4; ++e) { v0[e] = sigmoidf_(v0[e]); v1[e] = sigmoidf_(v1[e]); }
;                             *(f32x4*)gn = v0; *(f32x4*)(gn + 4) = v1; }
.LBB0_395:
	v_cvt_pk_bf16_f32 v12, v12, v13
	v_cvt_pk_bf16_f32 v13, v14, v15
	v_cvt_pk_bf16_f32 v14, v8, v9
	v_lshlrev_b32_e32 v8, 8, v16
	v_and_b32_e32 v136, 0x3fef00, v8
	v_lshl_add_u64 v[8:9], v[66:67], 0, v[136:137]
	v_cvt_pk_bf16_f32 v15, v10, v11
	global_store_dwordx4 v[8:9], v[12:15], off nt
	v_or_b32_e32 v8, 0xb0, v150
	s_and_b64 vcc, exec, s[10:11]
	s_mov_b64 s[10:11], -1
	s_cbranch_vccnz .LBB0_288
.LBB0_396:
	s_and_b64 vcc, exec, s[8:9]
	s_mov_b64 s[8:9], -1
	s_cbranch_vccnz .LBB0_400
	s_and_saveexec_b64 s[8:9], s[4:5]
	s_cbranch_execz .LBB0_399
	v_mul_f32_e32 v9, 0xbfb8aa3b, v4
	v_exp_f32_e32 v9, v9
	v_mul_f32_e32 v10, 0xbfb8aa3b, v0
	v_exp_f32_e32 v10, v10
	v_mul_f32_e32 v12, 0xbfb8aa3b, v1
	v_add_f32_e32 v9, 1.0, v9
	v_exp_f32_e32 v12, v12
	v_add_f32_e32 v11, 1.0, v10
	v_rcp_f32_e32 v10, v9
	v_mul_f32_e32 v9, 0xbfb8aa3b, v5
	v_exp_f32_e32 v9, v9
	v_rcp_f32_e32 v14, v11
	v_mul_f32_e32 v13, 0xbfb8aa3b, v2
	v_exp_f32_e32 v13, v13
	v_add_f32_e32 v9, 1.0, v9
	v_rcp_f32_e32 v11, v9
	v_add_f32_e32 v9, 1.0, v12
	v_mul_f32_e32 v12, 0xbfb8aa3b, v6
	v_exp_f32_e32 v12, v12
	v_rcp_f32_e32 v15, v9
	v_mul_f32_e32 v16, 0xbfb8aa3b, v3
	v_exp_f32_e32 v17, v16
	v_add_f32_e32 v9, 1.0, v12
	v_rcp_f32_e32 v12, v9
	v_add_f32_e32 v9, 1.0, v13
	v_mul_f32_e32 v13, 0xbfb8aa3b, v7
	v_exp_f32_e32 v13, v13
	v_rcp_f32_e32 v16, v9
	v_mad_i64_i32 v[18:19], s[10:11], v8, s27, v[140:141]
	v_add_f32_e32 v9, 1.0, v13
	v_rcp_f32_e32 v13, v9
	v_add_f32_e32 v9, 1.0, v17
	v_rcp_f32_e32 v17, v9
	global_store_dwordx4 v[18:19], v[10:13], off nt
	global_store_dwordx4 v[18:19], v[14:17], off offset:16 nt
